# NSA: XCD-aware item remap + static s_setprio 2 for waves 0-3 during NSA attention
# speedup vs baseline: 1.0114x; 1.0114x over previous
; #define GSYNC() xcd_barrier(wv, xb)
; __global__ void __launch_bounds__(512, 2) mega_fwd(P p) {
;     ...
;           for (int rep = 0; rep < p.rep_cmp; ++rep) nsa_compress_phase(wv, p, lds);
;           GSYNC();
;           for (int rep = 0; rep < p.rep_nsa; ++rep) { if (rep) GSYNC(); nsa_attn_phase(wv, p, lds); }
;         }
.LBB0_601:
	s_setprio 0
	v_readlane_b32 s4, v252, 2
	s_add_i32 s45, s45, 1
	v_readlane_b32 s5, v252, 3
	s_cmp_eq_u32 s45, s4
	v_readlane_b32 s4, v252, 10
	v_readlane_b32 s5, v252, 11
	v_readlane_b32 s6, v252, 4
	v_readlane_b32 s7, v252, 5
	v_readlane_b32 s8, v252, 6
	v_readlane_b32 s9, v252, 7
	v_readlane_b32 s10, v252, 8
	v_readlane_b32 s11, v252, 9
	s_cbranch_scc1 .LBB0_812

; DI int lane_id_() { int l; asm volatile("v_mbcnt_lo_u32_b32 %0, -1, 0\n\tv_mbcnt_hi_u32_b32 %0, -1, %0" : "=v"(l)); return l; }
; #define GSYNC() xcd_barrier(wv, xb)
; DI void nsa_attn_phase(int wv, const P& p_, LAS unsigned char* lds) {
;     ...
;   for (int it = blockIdx.x; it < 2048; it += gridDim.x) {
;     int tid_ = wv * 64 + lane_id_(); asm volatile("" : "+v"(tid_)); const int tid = tid_, wid = wv, lane = tid & 63, r = lane & 31, h = lane >> 5, tl = r >> 2, hd = r & 3;
;     const int c = it & 255, ii = it >> 8, bg = c >> 3, b = bg >> 2, g = bg & 3, j8 = c & 7;
;     const int qi = (ii & 1) ? (16 * (ii >> 1) + 15 - j8) : (16 * (ii >> 1) + j8);
;     const int t0 = 64 * qi, tw = t0 + 8 * wid, t = tw + tl, head = g * 4 + hd;
; __global__ void __launch_bounds__(512, 2) mega_fwd(P p) {
;     ...
;           for (int rep = 0; rep < p.rep_cmp; ++rep) nsa_compress_phase(wv, p, lds);
;           GSYNC();
;           for (int rep = 0; rep < p.rep_nsa; ++rep) { if (rep) GSYNC(); nsa_attn_phase(wv, p, lds); }
;         }
.LBB0_657:
	v_readlane_b32 s4, v253, 12
	v_readlane_b32 s5, v253, 13
	s_mov_b64 s[0:1], 0
	s_andn2_b64 vcc, exec, s[4:5]
	s_cbranch_vccnz .LBB0_601
	v_readlane_b32 s8, v254, 27
	v_readlane_b32 s22, v254, 41
	v_readlane_b32 s23, v254, 42
	s_add_u32 s6, s22, s0
	s_addc_u32 s7, s23, s1
	s_add_u32 s82, s6, 0x7000000
	s_addc_u32 s83, s7, 0
	s_add_u32 s62, s6, 0x1b000000
	s_addc_u32 s63, s7, 0
	s_add_u32 s54, s6, 0x1f440000
	s_addc_u32 s51, s7, 0
	s_add_u32 s33, s6, 0x1f540000
	s_addc_u32 s49, s7, 0
	s_add_u32 s28, s6, 0x2c27800
	s_addc_u32 s29, s7, 0
	v_readlane_b32 s4, v254, 6
	s_add_u32 s46, s4, s0
	v_readlane_b32 s0, v254, 7
	s_addc_u32 s47, s0, s1
	v_readlane_b32 s0, v252, 14
	s_and_b32 s94, s0, 7
	s_lshl_b32 s94, s94, 5
	s_lshr_b32 s4, s0, 3
	s_or_b32 s94, s94, s4
	s_cmpk_eq_u32 s68, 0x100
	s_cselect_b32 s94, s94, s0
	s_cmpk_lt_u32 s69, 0x100
	s_cbranch_scc0 .Lnsa_prio_skip
	s_setprio 2
.Lnsa_prio_skip:
	v_readlane_b32 s4, v254, 53
	v_readlane_b32 s5, v254, 45
	v_readlane_b32 s9, v254, 28
	v_readlane_b32 s10, v254, 29
	v_readlane_b32 s11, v254, 30
	v_readlane_b32 s12, v254, 31
	v_readlane_b32 s13, v254, 32
	v_readlane_b32 s14, v254, 33
	v_readlane_b32 s15, v254, 34
	v_readlane_b32 s16, v254, 35
	v_readlane_b32 s17, v254, 36
	v_readlane_b32 s18, v254, 37
	v_readlane_b32 s19, v254, 38
	v_readlane_b32 s20, v254, 39
	v_readlane_b32 s21, v254, 40
	v_readlane_b32 s1, v252, 15
	s_branch .LBB0_660
